# fp8 down-GEMM K-loops rescheduled to 16-MFMA super-phases (as the bf16 loops) + S5 3-deep u prefetch ring
# speedup vs baseline: 1.0036x; 1.0036x over previous
.LBB0_636:
	v_and_b32_e32 v3, 48, v2
	v_lshlrev_b32_e32 v4, 6, v2
	s_movk_i32 s3, 0x3c0
	v_lshlrev_b32_e32 v2, 2, v2
	s_and_b32 s67, s14, 3
	s_lshl_b32 s2, s15, 13
	v_and_or_b32 v3, v4, s3, v3
	v_and_b32_e32 v2, 32, v2
	s_lshl_b32 s64, s15, 6
	v_bitop3_b32 v4, v3, s2, v2 bitop3:0xde
	s_lshl_b32 s2, s67, 12
	s_add_u32 s34, s6, 0x80
	s_addc_u32 s35, s7, 0
	s_add_i32 s81, s73, 0x18000
	v_bitop3_b32 v2, v3, s2, v2 bitop3:0xde
	s_waitcnt vmcnt(2)
	s_barrier
	s_mov_b32 s2, m0
	s_mov_b32 m0, s81
	s_nop 4
	global_load_lds_dwordx4 v131, s[34:35]
	s_mov_b32 m0, s2
	s_add_u32 s34, s6, 0x2c080
	s_addc_u32 s35, s7, 0
	s_add_i32 s82, s73, 0x1a000
	s_mov_b32 s2, m0
	s_mov_b32 m0, s82
	s_nop 4
	global_load_lds_dwordx4 v131, s[34:35]
	s_mov_b32 m0, s2
	s_add_u32 s34, s10, 0x80
	s_addc_u32 s35, s11, 0
	s_add_i32 s84, s73, 0x8000
	s_mov_b32 s2, m0
	s_mov_b32 m0, s84
	s_nop 4
	global_load_lds_dwordx4 v130, s[34:35]
	s_mov_b32 m0, s2
	s_add_u32 s34, s10, 0x2c080
	s_addc_u32 s35, s11, 0
	s_add_i32 s85, s73, 0xa000
	s_mov_b32 s2, m0
	s_mov_b32 m0, s85
	s_nop 4
	global_load_lds_dwordx4 v130, s[34:35]
	s_mov_b32 m0, s2
	s_add_u32 s34, s6, 0x58080
	s_addc_u32 s35, s7, 0
	s_add_i32 s86, s73, 0x1c000
	s_mov_b32 s2, m0
	s_mov_b32 m0, s86
	s_nop 4
	global_load_lds_dwordx4 v131, s[34:35]
	s_mov_b32 m0, s2
	s_add_u32 s34, s6, 0x84080
	s_addc_u32 s35, s7, 0
	s_add_i32 s87, s73, 0x1e000
	s_mov_b32 s2, m0
	s_mov_b32 m0, s87
	s_nop 4
	global_load_lds_dwordx4 v131, s[34:35]
	s_mov_b32 m0, s2
	s_waitcnt vmcnt(6)
	s_add_i32 s88, s73, 0xc000
	s_add_u32 s89, s62, s1
	v_mov_b32_e32 v110, 0
	v_add_u32_e32 v2, 0, v2
	s_addc_u32 s90, s63, s0
	s_mov_b32 s91, -2
	v_add_u32_e32 v132, 0x10000, v2
	v_add_u32_e32 v133, 0, v4
	v_add_u32_e32 v134, 0x14000, v2
	v_add_u32_e32 v135, 0x18000, v2
	v_add_u32_e32 v136, 0x1c000, v2
	s_mov_b64 s[34:35], s[10:11]
	v_mov_b32_e32 v111, v110
	v_mov_b32_e32 v112, v110
	v_mov_b32_e32 v113, v110
	v_mov_b32_e32 v118, v110
	v_mov_b32_e32 v119, v110
	v_mov_b32_e32 v120, v110
	v_mov_b32_e32 v121, v110
	v_mov_b32_e32 v102, v110
	v_mov_b32_e32 v103, v110
	v_mov_b32_e32 v104, v110
	v_mov_b32_e32 v105, v110
	v_mov_b32_e32 v106, v110
	v_mov_b32_e32 v107, v110
	v_mov_b32_e32 v108, v110
	v_mov_b32_e32 v109, v110
	v_mov_b32_e32 v82, v110
	v_mov_b32_e32 v83, v110
	v_mov_b32_e32 v84, v110
	v_mov_b32_e32 v85, v110
	v_mov_b32_e32 v86, v110
	v_mov_b32_e32 v87, v110
	v_mov_b32_e32 v88, v110
	v_mov_b32_e32 v89, v110
	v_mov_b32_e32 v66, v110
	v_mov_b32_e32 v67, v110
	v_mov_b32_e32 v68, v110
	v_mov_b32_e32 v69, v110
	v_mov_b32_e32 v70, v110
	v_mov_b32_e32 v71, v110
	v_mov_b32_e32 v72, v110
	v_mov_b32_e32 v73, v110
	v_mov_b32_e32 v122, v110
	v_mov_b32_e32 v123, v110
	v_mov_b32_e32 v124, v110
	v_mov_b32_e32 v125, v110
	v_mov_b32_e32 v98, v110
	v_mov_b32_e32 v99, v110
	v_mov_b32_e32 v100, v110
	v_mov_b32_e32 v101, v110
	v_mov_b32_e32 v114, v110
	v_mov_b32_e32 v115, v110
	v_mov_b32_e32 v116, v110
	v_mov_b32_e32 v117, v110
	v_mov_b32_e32 v126, v110
	v_mov_b32_e32 v127, v110
	v_mov_b32_e32 v128, v110
	v_mov_b32_e32 v129, v110
	v_mov_b32_e32 v90, v110
	v_mov_b32_e32 v91, v110
	v_mov_b32_e32 v92, v110
	v_mov_b32_e32 v93, v110
	v_mov_b32_e32 v94, v110
	v_mov_b32_e32 v95, v110
	v_mov_b32_e32 v96, v110
	v_mov_b32_e32 v97, v110
	v_mov_b32_e32 v74, v110
	v_mov_b32_e32 v75, v110
	v_mov_b32_e32 v76, v110
	v_mov_b32_e32 v77, v110
	v_mov_b32_e32 v78, v110
	v_mov_b32_e32 v79, v110
	v_mov_b32_e32 v80, v110
	v_mov_b32_e32 v81, v110
	v_mov_b32_e32 v46, v110
	v_mov_b32_e32 v47, v110
	v_mov_b32_e32 v48, v110
	v_mov_b32_e32 v49, v110
	v_mov_b32_e32 v54, v110
	v_mov_b32_e32 v55, v110
	v_mov_b32_e32 v56, v110
	v_mov_b32_e32 v57, v110
	s_waitcnt lgkmcnt(0)
	v_mov_b32_e32 v34, v110
	v_mov_b32_e32 v35, v110
	v_mov_b32_e32 v36, v110
	v_mov_b32_e32 v37, v110
	v_mov_b32_e32 v38, v110
	v_mov_b32_e32 v39, v110
	v_mov_b32_e32 v40, v110
	v_mov_b32_e32 v41, v110
	v_mov_b32_e32 v18, v110
	v_mov_b32_e32 v19, v110
	v_mov_b32_e32 v20, v110
	v_mov_b32_e32 v21, v110
	v_mov_b32_e32 v22, v110
	v_mov_b32_e32 v23, v110
	v_mov_b32_e32 v24, v110
	v_mov_b32_e32 v25, v110
	v_mov_b32_e32 v2, v110
	v_mov_b32_e32 v3, v110
	v_mov_b32_e32 v4, v110
	v_mov_b32_e32 v5, v110
	v_mov_b32_e32 v6, v110
	v_mov_b32_e32 v7, v110
	v_mov_b32_e32 v8, v110
	v_mov_b32_e32 v9, v110
	v_mov_b32_e32 v58, v110
	v_mov_b32_e32 v59, v110
	v_mov_b32_e32 v60, v110
	v_mov_b32_e32 v61, v110
	v_mov_b32_e32 v62, v110
	v_mov_b32_e32 v63, v110
	v_mov_b32_e32 v64, v110
	v_mov_b32_e32 v65, v110
	v_mov_b32_e32 v42, v110
	v_mov_b32_e32 v43, v110
	v_mov_b32_e32 v44, v110
	v_mov_b32_e32 v45, v110
	v_mov_b32_e32 v50, v110
	v_mov_b32_e32 v51, v110
	v_mov_b32_e32 v52, v110
	v_mov_b32_e32 v53, v110
	v_mov_b32_e32 v26, v110
	v_mov_b32_e32 v27, v110
	v_mov_b32_e32 v28, v110
	v_mov_b32_e32 v29, v110
	v_mov_b32_e32 v30, v110
	v_mov_b32_e32 v31, v110
	v_mov_b32_e32 v32, v110
	v_mov_b32_e32 v33, v110
	v_mov_b32_e32 v10, v110
	v_mov_b32_e32 v11, v110
	v_mov_b32_e32 v12, v110
	v_mov_b32_e32 v13, v110
	v_mov_b32_e32 v14, v110
	v_mov_b32_e32 v15, v110
	v_mov_b32_e32 v16, v110
	v_mov_b32_e32 v17, v110
	s_barrier
.LBB0_637:
	ds_read_b128 v[138:141], v132
	ds_read_b128 v[142:145], v132 offset:1024
	ds_read_b128 v[146:149], v132 offset:2048
	ds_read_b128 v[150:153], v132 offset:3072
	ds_read_b128 v[154:157], v134
	ds_read_b128 v[158:161], v134 offset:1024
	ds_read_b128 v[182:185], v134 offset:2048
	ds_read_b128 v[186:189], v134 offset:3072
	s_add_u32 s0, s34, 0x100
	s_addc_u32 s1, s35, 0
	s_cmp_eq_u32 s91, 18
	s_cselect_b32 s52, s10, s0
	s_cselect_b32 s53, s11, s1
	s_cselect_b32 s50, s6, s89
	s_cselect_b32 s51, s7, s90
	s_add_u32 s54, s52, 0x80
	s_addc_u32 s55, s53, 0
	s_add_u32 s92, s34, 0x58080
	s_addc_u32 s93, s35, 0
	s_mov_b32 m0, s88
	s_nop 4
	global_load_lds_dwordx4 v130, s[92:93]
	s_add_u32 s34, s34, 0x84080
	s_addc_u32 s35, s35, 0
	s_add_i32 s2, s73, 0xe000
	s_mov_b32 m0, s2
	s_nop 4
	global_load_lds_dwordx4 v130, s[34:35]
	ds_read_b128 v[190:193], v133
	ds_read_b128 v[194:197], v133 offset:1024
	ds_read_b128 v[198:201], v133 offset:2048
	ds_read_b128 v[202:205], v133 offset:3072
	ds_read_b128 v[206:209], v133 offset:4096
	ds_read_b128 v[210:213], v133 offset:5120
	ds_read_b128 v[214:217], v133 offset:6144
	ds_read_b128 v[218:221], v133 offset:7168
	s_waitcnt vmcnt(8)
	s_waitcnt lgkmcnt(0)
	s_barrier
	s_setprio 1
	v_mfma_f32_16x16x128_f8f6f4 v[14:17], v[138:145], v[190:197], v[14:17]
	v_mfma_f32_16x16x128_f8f6f4 v[30:33], v[138:145], v[198:205], v[30:33]
	v_mfma_f32_16x16x128_f8f6f4 v[50:53], v[138:145], v[206:213], v[50:53]
	v_mfma_f32_16x16x128_f8f6f4 v[62:65], v[138:145], v[214:221], v[62:65]
	v_mfma_f32_16x16x128_f8f6f4 v[10:13], v[146:153], v[190:197], v[10:13]
	v_mfma_f32_16x16x128_f8f6f4 v[26:29], v[146:153], v[198:205], v[26:29]
	v_mfma_f32_16x16x128_f8f6f4 v[42:45], v[146:153], v[206:213], v[42:45]
	v_mfma_f32_16x16x128_f8f6f4 v[58:61], v[146:153], v[214:221], v[58:61]
	s_setprio 0
	s_setprio 1
	v_mfma_f32_16x16x128_f8f6f4 v[6:9], v[154:161], v[190:197], v[6:9]
	v_mfma_f32_16x16x128_f8f6f4 v[22:25], v[154:161], v[198:205], v[22:25]
	v_mfma_f32_16x16x128_f8f6f4 v[38:41], v[154:161], v[206:213], v[38:41]
	v_mfma_f32_16x16x128_f8f6f4 v[54:57], v[154:161], v[214:221], v[54:57]
	v_mfma_f32_16x16x128_f8f6f4 v[2:5], v[182:189], v[190:197], v[2:5]
	v_mfma_f32_16x16x128_f8f6f4 v[18:21], v[182:189], v[198:205], v[18:21]
	v_mfma_f32_16x16x128_f8f6f4 v[34:37], v[182:189], v[206:213], v[34:37]
	v_mfma_f32_16x16x128_f8f6f4 v[46:49], v[182:189], v[214:221], v[46:49]
	s_setprio 0
	s_barrier
	ds_read_b128 v[190:193], v133 offset:16384
	ds_read_b128 v[194:197], v133 offset:17408
	ds_read_b128 v[198:201], v133 offset:18432
	ds_read_b128 v[202:205], v133 offset:19456
	ds_read_b128 v[206:209], v133 offset:20480
	ds_read_b128 v[210:213], v133 offset:21504
	ds_read_b128 v[214:217], v133 offset:22528
	ds_read_b128 v[218:221], v133 offset:23552
	s_mov_b32 m0, s74
	s_nop 4
	global_load_lds_dwordx4 v131, s[50:51]
	s_add_u32 s34, s50, 0x2c000
	s_addc_u32 s35, s51, 0
	s_mov_b32 m0, s75
	s_nop 4
	global_load_lds_dwordx4 v131, s[34:35]
	s_add_u32 s34, s50, 0x58000
	s_addc_u32 s35, s51, 0
	s_mov_b32 m0, s77
	s_nop 4
	global_load_lds_dwordx4 v131, s[34:35]
	s_add_u32 s34, s50, 0x84000
	s_addc_u32 s35, s51, 0
	s_mov_b32 m0, s78
	s_nop 4
	global_load_lds_dwordx4 v131, s[34:35]
	s_mov_b32 m0, s73
	s_nop 4
	global_load_lds_dwordx4 v130, s[52:53]
	s_add_u32 s34, s52, 0x2c000
	s_addc_u32 s35, s53, 0
	s_mov_b32 m0, s76
	s_nop 4
	global_load_lds_dwordx4 v130, s[34:35]
	s_waitcnt vmcnt(8)
	s_waitcnt lgkmcnt(0)
	s_barrier
	s_setprio 1
	v_mfma_f32_16x16x128_f8f6f4 v[78:81], v[138:145], v[190:197], v[78:81]
	v_mfma_f32_16x16x128_f8f6f4 v[94:97], v[138:145], v[198:205], v[94:97]
	v_mfma_f32_16x16x128_f8f6f4 v[126:129], v[138:145], v[206:213], v[126:129]
	v_mfma_f32_16x16x128_f8f6f4 v[98:101], v[138:145], v[214:221], v[98:101]
	v_mfma_f32_16x16x128_f8f6f4 v[74:77], v[146:153], v[190:197], v[74:77]
	v_mfma_f32_16x16x128_f8f6f4 v[90:93], v[146:153], v[198:205], v[90:93]
	v_mfma_f32_16x16x128_f8f6f4 v[114:117], v[146:153], v[206:213], v[114:117]
	v_mfma_f32_16x16x128_f8f6f4 v[122:125], v[146:153], v[214:221], v[122:125]
	s_setprio 0
	s_setprio 1
	v_mfma_f32_16x16x128_f8f6f4 v[70:73], v[154:161], v[190:197], v[70:73]
	v_mfma_f32_16x16x128_f8f6f4 v[86:89], v[154:161], v[198:205], v[86:89]
	v_mfma_f32_16x16x128_f8f6f4 v[106:109], v[154:161], v[206:213], v[106:109]
	v_mfma_f32_16x16x128_f8f6f4 v[118:121], v[154:161], v[214:221], v[118:121]
	v_mfma_f32_16x16x128_f8f6f4 v[66:69], v[182:189], v[190:197], v[66:69]
	v_mfma_f32_16x16x128_f8f6f4 v[82:85], v[182:189], v[198:205], v[82:85]
	v_mfma_f32_16x16x128_f8f6f4 v[102:105], v[182:189], v[206:213], v[102:105]
	v_mfma_f32_16x16x128_f8f6f4 v[110:113], v[182:189], v[214:221], v[110:113]
	s_setprio 0
	s_barrier
	ds_read_b128 v[138:141], v135
	ds_read_b128 v[142:145], v135 offset:1024
	ds_read_b128 v[146:149], v135 offset:2048
	ds_read_b128 v[150:153], v135 offset:3072
	ds_read_b128 v[154:157], v136
	ds_read_b128 v[158:161], v136 offset:1024
	ds_read_b128 v[182:185], v136 offset:2048
	ds_read_b128 v[186:189], v136 offset:3072
	s_add_u32 s34, s52, 0x58000
	s_addc_u32 s35, s53, 0
	s_mov_b32 m0, s79
	s_nop 4
	global_load_lds_dwordx4 v130, s[34:35]
	s_add_u32 s34, s52, 0x84000
	s_addc_u32 s35, s53, 0
	s_mov_b32 m0, s80
	s_nop 4
	global_load_lds_dwordx4 v130, s[34:35]
	ds_read_b128 v[190:193], v133 offset:32768
	ds_read_b128 v[194:197], v133 offset:33792
	ds_read_b128 v[198:201], v133 offset:34816
	ds_read_b128 v[202:205], v133 offset:35840
	ds_read_b128 v[206:209], v133 offset:36864
	ds_read_b128 v[210:213], v133 offset:37888
	ds_read_b128 v[214:217], v133 offset:38912
	ds_read_b128 v[218:221], v133 offset:39936
	s_waitcnt vmcnt(8)
	s_waitcnt lgkmcnt(0)
	s_barrier
	s_setprio 1
	v_mfma_f32_16x16x128_f8f6f4 v[14:17], v[138:145], v[190:197], v[14:17]
	v_mfma_f32_16x16x128_f8f6f4 v[30:33], v[138:145], v[198:205], v[30:33]
	v_mfma_f32_16x16x128_f8f6f4 v[50:53], v[138:145], v[206:213], v[50:53]
	v_mfma_f32_16x16x128_f8f6f4 v[62:65], v[138:145], v[214:221], v[62:65]
	v_mfma_f32_16x16x128_f8f6f4 v[10:13], v[146:153], v[190:197], v[10:13]
	v_mfma_f32_16x16x128_f8f6f4 v[26:29], v[146:153], v[198:205], v[26:29]
	v_mfma_f32_16x16x128_f8f6f4 v[42:45], v[146:153], v[206:213], v[42:45]
	v_mfma_f32_16x16x128_f8f6f4 v[58:61], v[146:153], v[214:221], v[58:61]
	s_setprio 0
	s_setprio 1
	v_mfma_f32_16x16x128_f8f6f4 v[6:9], v[154:161], v[190:197], v[6:9]
	v_mfma_f32_16x16x128_f8f6f4 v[22:25], v[154:161], v[198:205], v[22:25]
	v_mfma_f32_16x16x128_f8f6f4 v[38:41], v[154:161], v[206:213], v[38:41]
	v_mfma_f32_16x16x128_f8f6f4 v[54:57], v[154:161], v[214:221], v[54:57]
	v_mfma_f32_16x16x128_f8f6f4 v[2:5], v[182:189], v[190:197], v[2:5]
	v_mfma_f32_16x16x128_f8f6f4 v[18:21], v[182:189], v[198:205], v[18:21]
	v_mfma_f32_16x16x128_f8f6f4 v[34:37], v[182:189], v[206:213], v[34:37]
	v_mfma_f32_16x16x128_f8f6f4 v[46:49], v[182:189], v[214:221], v[46:49]
	s_setprio 0
	s_barrier
	ds_read_b128 v[190:193], v133 offset:49152
	ds_read_b128 v[194:197], v133 offset:50176
	ds_read_b128 v[198:201], v133 offset:51200
	ds_read_b128 v[202:205], v133 offset:52224
	ds_read_b128 v[206:209], v133 offset:53248
	ds_read_b128 v[210:213], v133 offset:54272
	ds_read_b128 v[214:217], v133 offset:55296
	ds_read_b128 v[218:221], v133 offset:56320
	s_add_u32 s34, s50, 0x80
	s_addc_u32 s35, s51, 0
	s_mov_b32 m0, s81
	s_nop 4
	global_load_lds_dwordx4 v131, s[34:35]
	s_add_u32 s34, s50, 0x2c080
	s_addc_u32 s35, s51, 0
	s_mov_b32 m0, s82
	s_nop 4
	global_load_lds_dwordx4 v131, s[34:35]
	s_add_u32 s34, s50, 0x58080
	s_addc_u32 s35, s51, 0
	s_mov_b32 m0, s86
	s_nop 4
	global_load_lds_dwordx4 v131, s[34:35]
	s_add_u32 s34, s50, 0x84080
	s_addc_u32 s35, s51, 0
	s_mov_b32 m0, s87
	s_nop 4
	global_load_lds_dwordx4 v131, s[34:35]
	s_mov_b32 m0, s84
	s_nop 4
	global_load_lds_dwordx4 v130, s[54:55]
	s_add_u32 s34, s52, 0x2c080
	s_addc_u32 s35, s53, 0
	s_mov_b32 m0, s85
	s_nop 4
	global_load_lds_dwordx4 v130, s[34:35]
	s_waitcnt vmcnt(8)
	s_waitcnt lgkmcnt(0)
	s_barrier
	s_setprio 1
	v_mfma_f32_16x16x128_f8f6f4 v[78:81], v[138:145], v[190:197], v[78:81]
	v_mfma_f32_16x16x128_f8f6f4 v[94:97], v[138:145], v[198:205], v[94:97]
	v_mfma_f32_16x16x128_f8f6f4 v[126:129], v[138:145], v[206:213], v[126:129]
	v_mfma_f32_16x16x128_f8f6f4 v[98:101], v[138:145], v[214:221], v[98:101]
	v_mfma_f32_16x16x128_f8f6f4 v[74:77], v[146:153], v[190:197], v[74:77]
	v_mfma_f32_16x16x128_f8f6f4 v[90:93], v[146:153], v[198:205], v[90:93]
	v_mfma_f32_16x16x128_f8f6f4 v[114:117], v[146:153], v[206:213], v[114:117]
	v_mfma_f32_16x16x128_f8f6f4 v[122:125], v[146:153], v[214:221], v[122:125]
	s_setprio 0
	s_setprio 1
	v_mfma_f32_16x16x128_f8f6f4 v[70:73], v[154:161], v[190:197], v[70:73]
	v_mfma_f32_16x16x128_f8f6f4 v[86:89], v[154:161], v[198:205], v[86:89]
	v_mfma_f32_16x16x128_f8f6f4 v[106:109], v[154:161], v[206:213], v[106:109]
	v_mfma_f32_16x16x128_f8f6f4 v[118:121], v[154:161], v[214:221], v[118:121]
	v_mfma_f32_16x16x128_f8f6f4 v[66:69], v[182:189], v[190:197], v[66:69]
	v_mfma_f32_16x16x128_f8f6f4 v[82:85], v[182:189], v[198:205], v[82:85]
	v_mfma_f32_16x16x128_f8f6f4 v[102:105], v[182:189], v[206:213], v[102:105]
	v_mfma_f32_16x16x128_f8f6f4 v[110:113], v[182:189], v[214:221], v[110:113]
	s_setprio 0
	s_add_i32 s91, s91, 2
	s_add_u32 s89, s89, 0x100
	s_addc_u32 s90, s90, 0
	s_cmp_lt_u32 s91, 20
	s_mov_b64 s[34:35], s[0:1]
	s_barrier
	s_cbranch_scc1 .LBB0_637
	s_waitcnt vmcnt(0)
	s_cmpk_gt_u32 s66, 0xff
	s_cbranch_scc1 .LBB0_640
	s_barrier

.LBB0_874:
	v_and_b32_e32 v3, 48, v2
	v_lshlrev_b32_e32 v4, 6, v2
	s_movk_i32 s13, 0x3c0
	v_lshlrev_b32_e32 v2, 2, v2
	s_and_b32 s65, s14, 3
	s_lshl_b32 s12, s15, 13
	v_and_or_b32 v3, v4, s13, v3
	v_and_b32_e32 v2, 32, v2
	s_lshl_b32 s62, s15, 6
	v_bitop3_b32 v4, v3, s12, v2 bitop3:0xde
	s_lshl_b32 s12, s65, 12
	s_add_u32 s34, s4, 0x80
	s_addc_u32 s35, s5, 0
	s_add_i32 s88, s66, 0x18000
	v_bitop3_b32 v2, v3, s12, v2 bitop3:0xde
	s_waitcnt vmcnt(2)
	s_barrier
	s_mov_b32 s12, m0
	s_mov_b32 m0, s88
	s_nop 4
	global_load_lds_dwordx4 v131, s[34:35]
	s_mov_b32 m0, s12
	s_add_u32 s34, s4, 0x2c080
	s_addc_u32 s35, s5, 0
	s_add_i32 s89, s66, 0x1a000
	s_mov_b32 s12, m0
	s_mov_b32 m0, s89
	s_nop 4
	global_load_lds_dwordx4 v131, s[34:35]
	s_mov_b32 m0, s12
	s_add_u32 s34, s8, 0x80
	s_addc_u32 s35, s9, 0
	s_add_i32 s90, s66, 0x8000
	s_mov_b32 s12, m0
	s_mov_b32 m0, s90
	s_nop 4
	global_load_lds_dwordx4 v130, s[34:35]
	s_mov_b32 m0, s12
	s_add_u32 s34, s8, 0x2c080
	s_addc_u32 s35, s9, 0
	s_add_i32 s91, s66, 0xa000
	s_mov_b32 s12, m0
	s_mov_b32 m0, s91
	s_nop 4
	global_load_lds_dwordx4 v130, s[34:35]
	s_mov_b32 m0, s12
	s_add_u32 s34, s4, 0x58080
	s_addc_u32 s35, s5, 0
	s_add_i32 s92, s66, 0x1c000
	s_mov_b32 s12, m0
	s_mov_b32 m0, s92
	s_nop 4
	global_load_lds_dwordx4 v131, s[34:35]
	s_mov_b32 m0, s12
	s_add_u32 s34, s4, 0x84080
	s_addc_u32 s35, s5, 0
	s_add_i32 s93, s66, 0x1e000
	s_mov_b32 s12, m0
	s_mov_b32 m0, s93
	s_nop 4
	global_load_lds_dwordx4 v131, s[34:35]
	s_mov_b32 m0, s12
	s_waitcnt vmcnt(6)
	s_add_i32 s94, s66, 0xc000
	s_add_u32 s95, s60, s1
	v_mov_b32_e32 v110, 0
	v_add_u32_e32 v2, 0, v2
	s_addc_u32 s96, s61, s0
	s_mov_b32 s97, -2
	v_add_u32_e32 v132, 0x10000, v2
	v_add_u32_e32 v133, 0, v4
	v_add_u32_e32 v134, 0x14000, v2
	v_add_u32_e32 v135, 0x18000, v2
	v_add_u32_e32 v136, 0x1c000, v2
	s_mov_b64 s[34:35], s[8:9]
	v_mov_b32_e32 v111, v110
	v_mov_b32_e32 v112, v110
	v_mov_b32_e32 v113, v110
	v_mov_b32_e32 v118, v110
	v_mov_b32_e32 v119, v110
	v_mov_b32_e32 v120, v110
	v_mov_b32_e32 v121, v110
	v_mov_b32_e32 v102, v110
	v_mov_b32_e32 v103, v110
	v_mov_b32_e32 v104, v110
	v_mov_b32_e32 v105, v110
	v_mov_b32_e32 v106, v110
	v_mov_b32_e32 v107, v110
	v_mov_b32_e32 v108, v110
	v_mov_b32_e32 v109, v110
	v_mov_b32_e32 v82, v110
	v_mov_b32_e32 v83, v110
	v_mov_b32_e32 v84, v110
	v_mov_b32_e32 v85, v110
	v_mov_b32_e32 v86, v110
	v_mov_b32_e32 v87, v110
	v_mov_b32_e32 v88, v110
	v_mov_b32_e32 v89, v110
	v_mov_b32_e32 v66, v110
	v_mov_b32_e32 v67, v110
	v_mov_b32_e32 v68, v110
	v_mov_b32_e32 v69, v110
	v_mov_b32_e32 v70, v110
	v_mov_b32_e32 v71, v110
	v_mov_b32_e32 v72, v110
	v_mov_b32_e32 v73, v110
	v_mov_b32_e32 v122, v110
	v_mov_b32_e32 v123, v110
	v_mov_b32_e32 v124, v110
	v_mov_b32_e32 v125, v110
	v_mov_b32_e32 v98, v110
	v_mov_b32_e32 v99, v110
	v_mov_b32_e32 v100, v110
	v_mov_b32_e32 v101, v110
	v_mov_b32_e32 v114, v110
	v_mov_b32_e32 v115, v110
	v_mov_b32_e32 v116, v110
	v_mov_b32_e32 v117, v110
	v_mov_b32_e32 v126, v110
	v_mov_b32_e32 v127, v110
	v_mov_b32_e32 v128, v110
	v_mov_b32_e32 v129, v110
	v_mov_b32_e32 v90, v110
	v_mov_b32_e32 v91, v110
	v_mov_b32_e32 v92, v110
	v_mov_b32_e32 v93, v110
	v_mov_b32_e32 v94, v110
	v_mov_b32_e32 v95, v110
	v_mov_b32_e32 v96, v110
	v_mov_b32_e32 v97, v110
	v_mov_b32_e32 v74, v110
	v_mov_b32_e32 v75, v110
	v_mov_b32_e32 v76, v110
	v_mov_b32_e32 v77, v110
	v_mov_b32_e32 v78, v110
	v_mov_b32_e32 v79, v110
	v_mov_b32_e32 v80, v110
	v_mov_b32_e32 v81, v110
	v_mov_b32_e32 v46, v110
	v_mov_b32_e32 v47, v110
	v_mov_b32_e32 v48, v110
	v_mov_b32_e32 v49, v110
	v_mov_b32_e32 v54, v110
	v_mov_b32_e32 v55, v110
	v_mov_b32_e32 v56, v110
	v_mov_b32_e32 v57, v110
	s_waitcnt lgkmcnt(0)
	v_mov_b32_e32 v34, v110
	v_mov_b32_e32 v35, v110
	v_mov_b32_e32 v36, v110
	v_mov_b32_e32 v37, v110
	v_mov_b32_e32 v38, v110
	v_mov_b32_e32 v39, v110
	v_mov_b32_e32 v40, v110
	v_mov_b32_e32 v41, v110
	v_mov_b32_e32 v18, v110
	v_mov_b32_e32 v19, v110
	v_mov_b32_e32 v20, v110
	v_mov_b32_e32 v21, v110
	v_mov_b32_e32 v22, v110
	v_mov_b32_e32 v23, v110
	v_mov_b32_e32 v24, v110
	v_mov_b32_e32 v25, v110
	v_mov_b32_e32 v2, v110
	v_mov_b32_e32 v3, v110
	v_mov_b32_e32 v4, v110
	v_mov_b32_e32 v5, v110
	v_mov_b32_e32 v6, v110
	v_mov_b32_e32 v7, v110
	v_mov_b32_e32 v8, v110
	v_mov_b32_e32 v9, v110
	v_mov_b32_e32 v58, v110
	v_mov_b32_e32 v59, v110
	v_mov_b32_e32 v60, v110
	v_mov_b32_e32 v61, v110
	v_mov_b32_e32 v62, v110
	v_mov_b32_e32 v63, v110
	v_mov_b32_e32 v64, v110
	v_mov_b32_e32 v65, v110
	v_mov_b32_e32 v42, v110
	v_mov_b32_e32 v43, v110
	v_mov_b32_e32 v44, v110
	v_mov_b32_e32 v45, v110
	v_mov_b32_e32 v50, v110
	v_mov_b32_e32 v51, v110
	v_mov_b32_e32 v52, v110
	v_mov_b32_e32 v53, v110
	v_mov_b32_e32 v26, v110
	v_mov_b32_e32 v27, v110
	v_mov_b32_e32 v28, v110
	v_mov_b32_e32 v29, v110
	v_mov_b32_e32 v30, v110
	v_mov_b32_e32 v31, v110
	v_mov_b32_e32 v32, v110
	v_mov_b32_e32 v33, v110
	v_mov_b32_e32 v10, v110
	v_mov_b32_e32 v11, v110
	v_mov_b32_e32 v12, v110
	v_mov_b32_e32 v13, v110
	v_mov_b32_e32 v14, v110
	v_mov_b32_e32 v15, v110
	v_mov_b32_e32 v16, v110
	v_mov_b32_e32 v17, v110
	s_barrier
.LBB0_875:
	ds_read_b128 v[138:141], v132
	ds_read_b128 v[142:145], v132 offset:1024
	ds_read_b128 v[146:149], v132 offset:2048
	ds_read_b128 v[150:153], v132 offset:3072
	ds_read_b128 v[154:157], v134
	ds_read_b128 v[158:161], v134 offset:1024
	ds_read_b128 v[182:185], v134 offset:2048
	ds_read_b128 v[186:189], v134 offset:3072
	s_add_u32 s0, s34, 0x100
	s_addc_u32 s1, s35, 0
	s_cmp_eq_u32 s97, 18
	s_cselect_b32 s50, s8, s0
	s_cselect_b32 s51, s9, s1
	s_cselect_b32 s44, s4, s95
	s_cselect_b32 s45, s5, s96
	s_add_u32 s52, s50, 0x80
	s_addc_u32 s53, s51, 0
	s_add_u32 s12, s34, 0x58080
	s_addc_u32 s13, s35, 0
	s_mov_b32 m0, s94
	s_nop 4
	global_load_lds_dwordx4 v130, s[12:13]
	s_add_u32 s12, s34, 0x84080
	s_addc_u32 s13, s35, 0
	s_add_i32 s34, s66, 0xe000
	s_mov_b32 m0, s34
	s_nop 4
	global_load_lds_dwordx4 v130, s[12:13]
	ds_read_b128 v[190:193], v133
	ds_read_b128 v[194:197], v133 offset:1024
	ds_read_b128 v[198:201], v133 offset:2048
	ds_read_b128 v[202:205], v133 offset:3072
	ds_read_b128 v[206:209], v133 offset:4096
	ds_read_b128 v[210:213], v133 offset:5120
	ds_read_b128 v[214:217], v133 offset:6144
	ds_read_b128 v[218:221], v133 offset:7168
	s_waitcnt vmcnt(8)
	s_waitcnt lgkmcnt(0)
	s_barrier
	s_setprio 1
	v_mfma_f32_16x16x128_f8f6f4 v[14:17], v[138:145], v[190:197], v[14:17]
	v_mfma_f32_16x16x128_f8f6f4 v[30:33], v[138:145], v[198:205], v[30:33]
	v_mfma_f32_16x16x128_f8f6f4 v[50:53], v[138:145], v[206:213], v[50:53]
	v_mfma_f32_16x16x128_f8f6f4 v[62:65], v[138:145], v[214:221], v[62:65]
	v_mfma_f32_16x16x128_f8f6f4 v[10:13], v[146:153], v[190:197], v[10:13]
	v_mfma_f32_16x16x128_f8f6f4 v[26:29], v[146:153], v[198:205], v[26:29]
	v_mfma_f32_16x16x128_f8f6f4 v[42:45], v[146:153], v[206:213], v[42:45]
	v_mfma_f32_16x16x128_f8f6f4 v[58:61], v[146:153], v[214:221], v[58:61]
	s_setprio 0
	s_setprio 1
	v_mfma_f32_16x16x128_f8f6f4 v[6:9], v[154:161], v[190:197], v[6:9]
	v_mfma_f32_16x16x128_f8f6f4 v[22:25], v[154:161], v[198:205], v[22:25]
	v_mfma_f32_16x16x128_f8f6f4 v[38:41], v[154:161], v[206:213], v[38:41]
	v_mfma_f32_16x16x128_f8f6f4 v[54:57], v[154:161], v[214:221], v[54:57]
	v_mfma_f32_16x16x128_f8f6f4 v[2:5], v[182:189], v[190:197], v[2:5]
	v_mfma_f32_16x16x128_f8f6f4 v[18:21], v[182:189], v[198:205], v[18:21]
	v_mfma_f32_16x16x128_f8f6f4 v[34:37], v[182:189], v[206:213], v[34:37]
	v_mfma_f32_16x16x128_f8f6f4 v[46:49], v[182:189], v[214:221], v[46:49]
	s_setprio 0
	s_barrier
	ds_read_b128 v[190:193], v133 offset:16384
	ds_read_b128 v[194:197], v133 offset:17408
	ds_read_b128 v[198:201], v133 offset:18432
	ds_read_b128 v[202:205], v133 offset:19456
	ds_read_b128 v[206:209], v133 offset:20480
	ds_read_b128 v[210:213], v133 offset:21504
	ds_read_b128 v[214:217], v133 offset:22528
	ds_read_b128 v[218:221], v133 offset:23552
	s_mov_b32 m0, s67
	s_nop 4
	global_load_lds_dwordx4 v131, s[44:45]
	s_add_u32 s12, s44, 0x2c000
	s_addc_u32 s13, s45, 0
	s_mov_b32 m0, s73
	s_nop 4
	global_load_lds_dwordx4 v131, s[12:13]
	s_add_u32 s12, s44, 0x58000
	s_addc_u32 s13, s45, 0
	s_mov_b32 m0, s84
	s_nop 4
	global_load_lds_dwordx4 v131, s[12:13]
	s_add_u32 s12, s44, 0x84000
	s_addc_u32 s13, s45, 0
	s_mov_b32 m0, s85
	s_nop 4
	global_load_lds_dwordx4 v131, s[12:13]
	s_mov_b32 m0, s66
	s_nop 4
	global_load_lds_dwordx4 v130, s[50:51]
	s_add_u32 s12, s50, 0x2c000
	s_addc_u32 s13, s51, 0
	s_mov_b32 m0, s82
	s_nop 4
	global_load_lds_dwordx4 v130, s[12:13]
	s_waitcnt vmcnt(8)
	s_waitcnt lgkmcnt(0)
	s_barrier
	s_setprio 1
	v_mfma_f32_16x16x128_f8f6f4 v[78:81], v[138:145], v[190:197], v[78:81]
	v_mfma_f32_16x16x128_f8f6f4 v[94:97], v[138:145], v[198:205], v[94:97]
	v_mfma_f32_16x16x128_f8f6f4 v[126:129], v[138:145], v[206:213], v[126:129]
	v_mfma_f32_16x16x128_f8f6f4 v[98:101], v[138:145], v[214:221], v[98:101]
	v_mfma_f32_16x16x128_f8f6f4 v[74:77], v[146:153], v[190:197], v[74:77]
	v_mfma_f32_16x16x128_f8f6f4 v[90:93], v[146:153], v[198:205], v[90:93]
	v_mfma_f32_16x16x128_f8f6f4 v[114:117], v[146:153], v[206:213], v[114:117]
	v_mfma_f32_16x16x128_f8f6f4 v[122:125], v[146:153], v[214:221], v[122:125]
	s_setprio 0
	s_setprio 1
	v_mfma_f32_16x16x128_f8f6f4 v[70:73], v[154:161], v[190:197], v[70:73]
	v_mfma_f32_16x16x128_f8f6f4 v[86:89], v[154:161], v[198:205], v[86:89]
	v_mfma_f32_16x16x128_f8f6f4 v[106:109], v[154:161], v[206:213], v[106:109]
	v_mfma_f32_16x16x128_f8f6f4 v[118:121], v[154:161], v[214:221], v[118:121]
	v_mfma_f32_16x16x128_f8f6f4 v[66:69], v[182:189], v[190:197], v[66:69]
	v_mfma_f32_16x16x128_f8f6f4 v[82:85], v[182:189], v[198:205], v[82:85]
	v_mfma_f32_16x16x128_f8f6f4 v[102:105], v[182:189], v[206:213], v[102:105]
	v_mfma_f32_16x16x128_f8f6f4 v[110:113], v[182:189], v[214:221], v[110:113]
	s_setprio 0
	s_barrier
	ds_read_b128 v[138:141], v135
	ds_read_b128 v[142:145], v135 offset:1024
	ds_read_b128 v[146:149], v135 offset:2048
	ds_read_b128 v[150:153], v135 offset:3072
	ds_read_b128 v[154:157], v136
	ds_read_b128 v[158:161], v136 offset:1024
	ds_read_b128 v[182:185], v136 offset:2048
	ds_read_b128 v[186:189], v136 offset:3072
	s_add_u32 s12, s50, 0x58000
	s_addc_u32 s13, s51, 0
	s_mov_b32 m0, s86
	s_nop 4
	global_load_lds_dwordx4 v130, s[12:13]
	s_add_u32 s12, s50, 0x84000
	s_addc_u32 s13, s51, 0
	s_mov_b32 m0, s87
	s_nop 4
	global_load_lds_dwordx4 v130, s[12:13]
	ds_read_b128 v[190:193], v133 offset:32768
	ds_read_b128 v[194:197], v133 offset:33792
	ds_read_b128 v[198:201], v133 offset:34816
	ds_read_b128 v[202:205], v133 offset:35840
	ds_read_b128 v[206:209], v133 offset:36864
	ds_read_b128 v[210:213], v133 offset:37888
	ds_read_b128 v[214:217], v133 offset:38912
	ds_read_b128 v[218:221], v133 offset:39936
	s_waitcnt vmcnt(8)
	s_waitcnt lgkmcnt(0)
	s_barrier
	s_setprio 1
	v_mfma_f32_16x16x128_f8f6f4 v[14:17], v[138:145], v[190:197], v[14:17]
	v_mfma_f32_16x16x128_f8f6f4 v[30:33], v[138:145], v[198:205], v[30:33]
	v_mfma_f32_16x16x128_f8f6f4 v[50:53], v[138:145], v[206:213], v[50:53]
	v_mfma_f32_16x16x128_f8f6f4 v[62:65], v[138:145], v[214:221], v[62:65]
	v_mfma_f32_16x16x128_f8f6f4 v[10:13], v[146:153], v[190:197], v[10:13]
	v_mfma_f32_16x16x128_f8f6f4 v[26:29], v[146:153], v[198:205], v[26:29]
	v_mfma_f32_16x16x128_f8f6f4 v[42:45], v[146:153], v[206:213], v[42:45]
	v_mfma_f32_16x16x128_f8f6f4 v[58:61], v[146:153], v[214:221], v[58:61]
	s_setprio 0
	s_setprio 1
	v_mfma_f32_16x16x128_f8f6f4 v[6:9], v[154:161], v[190:197], v[6:9]
	v_mfma_f32_16x16x128_f8f6f4 v[22:25], v[154:161], v[198:205], v[22:25]
	v_mfma_f32_16x16x128_f8f6f4 v[38:41], v[154:161], v[206:213], v[38:41]
	v_mfma_f32_16x16x128_f8f6f4 v[54:57], v[154:161], v[214:221], v[54:57]
	v_mfma_f32_16x16x128_f8f6f4 v[2:5], v[182:189], v[190:197], v[2:5]
	v_mfma_f32_16x16x128_f8f6f4 v[18:21], v[182:189], v[198:205], v[18:21]
	v_mfma_f32_16x16x128_f8f6f4 v[34:37], v[182:189], v[206:213], v[34:37]
	v_mfma_f32_16x16x128_f8f6f4 v[46:49], v[182:189], v[214:221], v[46:49]
	s_setprio 0
	s_barrier
	ds_read_b128 v[190:193], v133 offset:49152
	ds_read_b128 v[194:197], v133 offset:50176
	ds_read_b128 v[198:201], v133 offset:51200
	ds_read_b128 v[202:205], v133 offset:52224
	ds_read_b128 v[206:209], v133 offset:53248
	ds_read_b128 v[210:213], v133 offset:54272
	ds_read_b128 v[214:217], v133 offset:55296
	ds_read_b128 v[218:221], v133 offset:56320
	s_add_u32 s12, s44, 0x80
	s_addc_u32 s13, s45, 0
	s_mov_b32 m0, s88
	s_nop 4
	global_load_lds_dwordx4 v131, s[12:13]
	s_add_u32 s12, s44, 0x2c080
	s_addc_u32 s13, s45, 0
	s_mov_b32 m0, s89
	s_nop 4
	global_load_lds_dwordx4 v131, s[12:13]
	s_add_u32 s12, s44, 0x58080
	s_addc_u32 s13, s45, 0
	s_mov_b32 m0, s92
	s_nop 4
	global_load_lds_dwordx4 v131, s[12:13]
	s_add_u32 s12, s44, 0x84080
	s_addc_u32 s13, s45, 0
	s_mov_b32 m0, s93
	s_nop 4
	global_load_lds_dwordx4 v131, s[12:13]
	s_mov_b32 m0, s90
	s_nop 4
	global_load_lds_dwordx4 v130, s[52:53]
	s_add_u32 s12, s50, 0x2c080
	s_addc_u32 s13, s51, 0
	s_mov_b32 m0, s91
	s_nop 4
	global_load_lds_dwordx4 v130, s[12:13]
	s_waitcnt vmcnt(8)
	s_waitcnt lgkmcnt(0)
	s_barrier
	s_setprio 1
	v_mfma_f32_16x16x128_f8f6f4 v[78:81], v[138:145], v[190:197], v[78:81]
	v_mfma_f32_16x16x128_f8f6f4 v[94:97], v[138:145], v[198:205], v[94:97]
	v_mfma_f32_16x16x128_f8f6f4 v[126:129], v[138:145], v[206:213], v[126:129]
	v_mfma_f32_16x16x128_f8f6f4 v[98:101], v[138:145], v[214:221], v[98:101]
	v_mfma_f32_16x16x128_f8f6f4 v[74:77], v[146:153], v[190:197], v[74:77]
	v_mfma_f32_16x16x128_f8f6f4 v[90:93], v[146:153], v[198:205], v[90:93]
	v_mfma_f32_16x16x128_f8f6f4 v[114:117], v[146:153], v[206:213], v[114:117]
	v_mfma_f32_16x16x128_f8f6f4 v[122:125], v[146:153], v[214:221], v[122:125]
	s_setprio 0
	s_setprio 1
	v_mfma_f32_16x16x128_f8f6f4 v[70:73], v[154:161], v[190:197], v[70:73]
	v_mfma_f32_16x16x128_f8f6f4 v[86:89], v[154:161], v[198:205], v[86:89]
	v_mfma_f32_16x16x128_f8f6f4 v[106:109], v[154:161], v[206:213], v[106:109]
	v_mfma_f32_16x16x128_f8f6f4 v[118:121], v[154:161], v[214:221], v[118:121]
	v_mfma_f32_16x16x128_f8f6f4 v[66:69], v[182:189], v[190:197], v[66:69]
	v_mfma_f32_16x16x128_f8f6f4 v[82:85], v[182:189], v[198:205], v[82:85]
	v_mfma_f32_16x16x128_f8f6f4 v[102:105], v[182:189], v[206:213], v[102:105]
	v_mfma_f32_16x16x128_f8f6f4 v[110:113], v[182:189], v[214:221], v[110:113]
	s_setprio 0
	s_add_i32 s97, s97, 2
	s_add_u32 s95, s95, 0x100
	s_addc_u32 s96, s96, 0
	s_cmp_lt_u32 s97, 20
	s_mov_b64 s[34:35], s[0:1]
	s_barrier
	s_cbranch_scc1 .LBB0_875
	s_waitcnt vmcnt(0)
	s_cmpk_gt_u32 s64, 0xff
	s_cbranch_scc1 .LBB0_878
	s_barrier

.LBB0_1492:
	v_and_b32_e32 v3, 48, v2
	v_lshlrev_b32_e32 v4, 6, v2
	v_lshlrev_b32_e32 v2, 2, v2
	s_and_b32 s65, s63, 3
	s_lshl_b32 s36, s64, 13
	v_and_or_b32 v3, v4, s45, v3
	v_and_b32_e32 v2, 32, v2
	s_lshl_b32 s60, s64, 6
	v_bitop3_b32 v4, v3, s36, v2 bitop3:0xde
	s_lshl_b32 s36, s65, 12
	v_bitop3_b32 v2, v3, s36, v2 bitop3:0xde
	s_add_u32 s36, s2, 0x80
	s_addc_u32 s37, s3, 0
	s_add_i32 s78, s66, 0x18000
	s_waitcnt vmcnt(2)
	s_barrier
	s_mov_b32 s38, m0
	s_mov_b32 m0, s78
	s_nop 4
	global_load_lds_dwordx4 v131, s[36:37]
	s_mov_b32 m0, s38
	s_add_u32 s36, s2, 0x2c080
	s_addc_u32 s37, s3, 0
	s_add_i32 s79, s66, 0x1a000
	s_mov_b32 s38, m0
	s_mov_b32 m0, s79
	s_nop 4
	global_load_lds_dwordx4 v131, s[36:37]
	s_mov_b32 m0, s38
	s_add_u32 s36, s6, 0x80
	s_addc_u32 s37, s7, 0
	s_add_i32 s80, s66, 0x8000
	s_mov_b32 s38, m0
	s_mov_b32 m0, s80
	s_nop 4
	global_load_lds_dwordx4 v130, s[36:37]
	s_mov_b32 m0, s38
	s_add_u32 s36, s6, 0x2c080
	s_addc_u32 s37, s7, 0
	s_add_i32 s81, s66, 0xa000
	s_mov_b32 s38, m0
	s_mov_b32 m0, s81
	s_nop 4
	global_load_lds_dwordx4 v130, s[36:37]
	s_mov_b32 m0, s38
	s_add_u32 s36, s2, 0x58080
	s_addc_u32 s37, s3, 0
	s_add_i32 s82, s66, 0x1c000
	s_mov_b32 s38, m0
	s_mov_b32 m0, s82
	s_nop 4
	global_load_lds_dwordx4 v131, s[36:37]
	s_mov_b32 m0, s38
	s_add_u32 s36, s2, 0x84080
	s_addc_u32 s37, s3, 0
	s_add_i32 s83, s66, 0x1e000
	s_mov_b32 s38, m0
	s_mov_b32 m0, s83
	s_nop 4
	global_load_lds_dwordx4 v131, s[36:37]
	s_mov_b32 m0, s38
	s_waitcnt vmcnt(6)
	s_add_i32 s84, s66, 0xc000
	s_add_u32 s85, s58, s35
	v_mov_b32_e32 v34, 0
	v_add_u32_e32 v2, 0, v2
	s_addc_u32 s86, s59, s34
	s_mov_b32 s87, -2
	v_add_u32_e32 v132, 0x10000, v2
	v_add_u32_e32 v133, 0, v4
	s_waitcnt vmcnt(32)
	v_add_u32_e32 v134, 0x14000, v2
	v_add_u32_e32 v135, 0x18000, v2
	v_add_u32_e32 v136, 0x1c000, v2
	s_mov_b64 s[36:37], s[6:7]
	v_mov_b32_e32 v35, v34
	v_mov_b32_e32 v36, v34
	v_mov_b32_e32 v37, v34
	v_mov_b32_e32 v170, v34
	v_mov_b32_e32 v171, v34
	v_mov_b32_e32 v172, v34
	v_mov_b32_e32 v173, v34
	v_mov_b32_e32 v2, v34
	v_mov_b32_e32 v3, v34
	v_mov_b32_e32 v4, v34
	v_mov_b32_e32 v5, v34
	v_mov_b32_e32 v6, v34
	v_mov_b32_e32 v7, v34
	v_mov_b32_e32 v8, v34
	v_mov_b32_e32 v9, v34
	v_mov_b32_e32 v10, v34
	v_mov_b32_e32 v11, v34
	v_mov_b32_e32 v12, v34
	v_mov_b32_e32 v13, v34
	v_mov_b32_e32 v14, v34
	v_mov_b32_e32 v15, v34
	v_mov_b32_e32 v16, v34
	v_mov_b32_e32 v17, v34
	v_mov_b32_e32 v26, v34
	v_mov_b32_e32 v27, v34
	v_mov_b32_e32 v28, v34
	v_mov_b32_e32 v29, v34
	v_mov_b32_e32 v30, v34
	v_mov_b32_e32 v31, v34
	v_mov_b32_e32 v32, v34
	v_mov_b32_e32 v33, v34
	v_mov_b32_e32 v46, v34
	v_mov_b32_e32 v47, v34
	v_mov_b32_e32 v48, v34
	v_mov_b32_e32 v49, v34
	v_mov_b32_e32 v54, v34
	v_mov_b32_e32 v55, v34
	v_mov_b32_e32 v56, v34
	v_mov_b32_e32 v57, v34
	v_mov_b32_e32 v18, v34
	v_mov_b32_e32 v19, v34
	v_mov_b32_e32 v20, v34
	v_mov_b32_e32 v21, v34
	v_mov_b32_e32 v22, v34
	v_mov_b32_e32 v23, v34
	v_mov_b32_e32 v24, v34
	v_mov_b32_e32 v25, v34
	v_mov_b32_e32 v38, v34
	v_mov_b32_e32 v39, v34
	v_mov_b32_e32 v40, v34
	v_mov_b32_e32 v41, v34
	v_mov_b32_e32 v50, v34
	v_mov_b32_e32 v51, v34
	v_mov_b32_e32 v52, v34
	v_mov_b32_e32 v53, v34
	v_mov_b32_e32 v66, v34
	v_mov_b32_e32 v67, v34
	v_mov_b32_e32 v68, v34
	v_mov_b32_e32 v69, v34
	v_mov_b32_e32 v70, v34
	v_mov_b32_e32 v71, v34
	v_mov_b32_e32 v72, v34
	v_mov_b32_e32 v73, v34
	v_mov_b32_e32 v42, v34
	v_mov_b32_e32 v43, v34
	v_mov_b32_e32 v44, v34
	v_mov_b32_e32 v45, v34
	v_mov_b32_e32 v62, v34
	v_mov_b32_e32 v63, v34
	v_mov_b32_e32 v64, v34
	v_mov_b32_e32 v65, v34
	v_mov_b32_e32 v74, v34
	v_mov_b32_e32 v75, v34
	v_mov_b32_e32 v76, v34
	v_mov_b32_e32 v77, v34
	v_mov_b32_e32 v78, v34
	v_mov_b32_e32 v79, v34
	v_mov_b32_e32 v80, v34
	v_mov_b32_e32 v81, v34
	v_mov_b32_e32 v90, v34
	v_mov_b32_e32 v91, v34
	v_mov_b32_e32 v92, v34
	v_mov_b32_e32 v93, v34
	v_mov_b32_e32 v94, v34
	v_mov_b32_e32 v95, v34
	v_mov_b32_e32 v96, v34
	v_mov_b32_e32 v97, v34
	v_mov_b32_e32 v106, v34
	v_mov_b32_e32 v107, v34
	v_mov_b32_e32 v108, v34
	v_mov_b32_e32 v109, v34
	v_mov_b32_e32 v110, v34
	v_mov_b32_e32 v111, v34
	v_mov_b32_e32 v112, v34
	v_mov_b32_e32 v113, v34
	v_mov_b32_e32 v82, v34
	v_mov_b32_e32 v83, v34
	v_mov_b32_e32 v84, v34
	v_mov_b32_e32 v85, v34
	v_mov_b32_e32 v86, v34
	v_mov_b32_e32 v87, v34
	v_mov_b32_e32 v88, v34
	v_mov_b32_e32 v89, v34
	v_mov_b32_e32 v98, v34
	v_mov_b32_e32 v99, v34
	v_mov_b32_e32 v100, v34
	v_mov_b32_e32 v101, v34
	v_mov_b32_e32 v102, v34
	v_mov_b32_e32 v103, v34
	v_mov_b32_e32 v104, v34
	v_mov_b32_e32 v105, v34
	v_mov_b32_e32 v114, v34
	v_mov_b32_e32 v115, v34
	v_mov_b32_e32 v116, v34
	v_mov_b32_e32 v117, v34
	v_mov_b32_e32 v118, v34
	v_mov_b32_e32 v119, v34
	v_mov_b32_e32 v120, v34
	v_mov_b32_e32 v121, v34
	v_mov_b32_e32 v122, v34
	v_mov_b32_e32 v123, v34
	v_mov_b32_e32 v124, v34
	v_mov_b32_e32 v125, v34
	v_mov_b32_e32 v126, v34
	v_mov_b32_e32 v127, v34
	v_mov_b32_e32 v128, v34
	v_mov_b32_e32 v129, v34
	s_barrier
.LBB0_1493:
	ds_read_b128 v[138:141], v132
	ds_read_b128 v[142:145], v132 offset:1024
	ds_read_b128 v[146:149], v132 offset:2048
	ds_read_b128 v[150:153], v132 offset:3072
	ds_read_b128 v[154:157], v134
	ds_read_b128 v[158:161], v134 offset:1024
	ds_read_b128 v[162:165], v134 offset:2048
	ds_read_b128 v[166:169], v134 offset:3072
	s_add_u32 s34, s36, 0x100
	s_addc_u32 s35, s37, 0
	s_cmp_eq_u32 s87, 18
	s_cselect_b32 s40, s6, s34
	s_cselect_b32 s41, s7, s35
	s_cselect_b32 s38, s2, s85
	s_cselect_b32 s39, s3, s86
	s_add_u32 s42, s40, 0x80
	s_addc_u32 s43, s41, 0
	s_add_u32 s88, s36, 0x58080
	s_addc_u32 s89, s37, 0
	s_mov_b32 m0, s84
	s_nop 4
	global_load_lds_dwordx4 v130, s[88:89]
	s_add_u32 s36, s36, 0x84080
	s_addc_u32 s37, s37, 0
	s_add_i32 s88, s66, 0xe000
	s_mov_b32 m0, s88
	s_nop 4
	global_load_lds_dwordx4 v130, s[36:37]
	ds_read_b128 v[176:179], v133
	ds_read_b128 v[180:183], v133 offset:1024
	ds_read_b128 v[186:189], v133 offset:2048
	ds_read_b128 v[190:193], v133 offset:3072
	ds_read_b128 v[194:197], v133 offset:4096
	ds_read_b128 v[198:201], v133 offset:5120
	ds_read_b128 v[202:205], v133 offset:6144
	ds_read_b128 v[206:209], v133 offset:7168
	s_waitcnt vmcnt(8)
	s_waitcnt lgkmcnt(0)
	s_barrier
	s_setprio 1
	v_mfma_f32_16x16x128_f8f6f4 v[126:129], v[138:145], v[176:183], v[126:129]
	v_mfma_f32_16x16x128_f8f6f4 v[118:121], v[138:145], v[186:193], v[118:121]
	v_mfma_f32_16x16x128_f8f6f4 v[102:105], v[138:145], v[194:201], v[102:105]
	v_mfma_f32_16x16x128_f8f6f4 v[86:89], v[138:145], v[202:209], v[86:89]
	v_mfma_f32_16x16x128_f8f6f4 v[122:125], v[146:153], v[176:183], v[122:125]
	v_mfma_f32_16x16x128_f8f6f4 v[114:117], v[146:153], v[186:193], v[114:117]
	v_mfma_f32_16x16x128_f8f6f4 v[98:101], v[146:153], v[194:201], v[98:101]
	v_mfma_f32_16x16x128_f8f6f4 v[82:85], v[146:153], v[202:209], v[82:85]
	s_setprio 0
	s_setprio 1
	v_mfma_f32_16x16x128_f8f6f4 v[110:113], v[154:161], v[176:183], v[110:113]
	v_mfma_f32_16x16x128_f8f6f4 v[94:97], v[154:161], v[186:193], v[94:97]
	v_mfma_f32_16x16x128_f8f6f4 v[78:81], v[154:161], v[194:201], v[78:81]
	v_mfma_f32_16x16x128_f8f6f4 v[62:65], v[154:161], v[202:209], v[62:65]
	v_mfma_f32_16x16x128_f8f6f4 v[106:109], v[162:169], v[176:183], v[106:109]
	v_mfma_f32_16x16x128_f8f6f4 v[90:93], v[162:169], v[186:193], v[90:93]
	v_mfma_f32_16x16x128_f8f6f4 v[74:77], v[162:169], v[194:201], v[74:77]
	v_mfma_f32_16x16x128_f8f6f4 v[42:45], v[162:169], v[202:209], v[42:45]
	s_setprio 0
	s_barrier
	ds_read_b128 v[176:179], v133 offset:16384
	ds_read_b128 v[180:183], v133 offset:17408
	ds_read_b128 v[186:189], v133 offset:18432
	ds_read_b128 v[190:193], v133 offset:19456
	ds_read_b128 v[194:197], v133 offset:20480
	ds_read_b128 v[198:201], v133 offset:21504
	ds_read_b128 v[202:205], v133 offset:22528
	ds_read_b128 v[206:209], v133 offset:23552
	s_nop 4
	s_mov_b32 m0, s67
	s_nop 4
	global_load_lds_dwordx4 v131, s[38:39]
	s_add_u32 s36, s38, 0x2c000
	s_addc_u32 s37, s39, 0
	s_mov_b32 m0, s72
	s_nop 4
	global_load_lds_dwordx4 v131, s[36:37]
	s_add_u32 s36, s38, 0x58000
	s_addc_u32 s37, s39, 0
	s_mov_b32 m0, s74
	s_nop 4
	global_load_lds_dwordx4 v131, s[36:37]
	s_add_u32 s36, s38, 0x84000
	s_addc_u32 s37, s39, 0
	s_mov_b32 m0, s75
	s_nop 4
	global_load_lds_dwordx4 v131, s[36:37]
	s_nop 2
	s_mov_b32 m0, s66
	s_nop 4
	global_load_lds_dwordx4 v130, s[40:41]
	s_add_u32 s36, s40, 0x2c000
	s_addc_u32 s37, s41, 0
	s_mov_b32 m0, s73
	s_nop 4
	global_load_lds_dwordx4 v130, s[36:37]
	s_waitcnt vmcnt(8)
	s_waitcnt lgkmcnt(0)
	s_barrier
	s_setprio 1
	v_mfma_f32_16x16x128_f8f6f4 v[70:73], v[138:145], v[176:183], v[70:73]
	v_mfma_f32_16x16x128_f8f6f4 v[50:53], v[138:145], v[186:193], v[50:53]
	v_mfma_f32_16x16x128_f8f6f4 v[22:25], v[138:145], v[194:201], v[22:25]
	v_mfma_f32_16x16x128_f8f6f4 v[54:57], v[138:145], v[202:209], v[54:57]
	v_mfma_f32_16x16x128_f8f6f4 v[66:69], v[146:153], v[176:183], v[66:69]
	v_mfma_f32_16x16x128_f8f6f4 v[38:41], v[146:153], v[186:193], v[38:41]
	v_mfma_f32_16x16x128_f8f6f4 v[18:21], v[146:153], v[194:201], v[18:21]
	v_mfma_f32_16x16x128_f8f6f4 v[46:49], v[146:153], v[202:209], v[46:49]
	s_setprio 0
	s_setprio 1
	v_mfma_f32_16x16x128_f8f6f4 v[30:33], v[154:161], v[176:183], v[30:33]
	v_mfma_f32_16x16x128_f8f6f4 v[14:17], v[154:161], v[186:193], v[14:17]
	v_mfma_f32_16x16x128_f8f6f4 v[6:9], v[154:161], v[194:201], v[6:9]
	v_mfma_f32_16x16x128_f8f6f4 v[170:173], v[154:161], v[202:209], v[170:173]
	v_mfma_f32_16x16x128_f8f6f4 v[26:29], v[162:169], v[176:183], v[26:29]
	v_mfma_f32_16x16x128_f8f6f4 v[10:13], v[162:169], v[186:193], v[10:13]
	v_mfma_f32_16x16x128_f8f6f4 v[2:5], v[162:169], v[194:201], v[2:5]
	v_mfma_f32_16x16x128_f8f6f4 v[34:37], v[162:169], v[202:209], v[34:37]
	s_setprio 0
	s_barrier
	ds_read_b128 v[138:141], v135
	ds_read_b128 v[142:145], v135 offset:1024
	ds_read_b128 v[146:149], v135 offset:2048
	ds_read_b128 v[150:153], v135 offset:3072
	ds_read_b128 v[154:157], v136
	ds_read_b128 v[158:161], v136 offset:1024
	ds_read_b128 v[162:165], v136 offset:2048
	ds_read_b128 v[166:169], v136 offset:3072
	s_nop 3
	s_add_u32 s36, s40, 0x58000
	s_addc_u32 s37, s41, 0
	s_mov_b32 m0, s76
	s_nop 4
	global_load_lds_dwordx4 v130, s[36:37]
	s_add_u32 s36, s40, 0x84000
	s_addc_u32 s37, s41, 0
	s_mov_b32 m0, s77
	s_nop 4
	global_load_lds_dwordx4 v130, s[36:37]
	ds_read_b128 v[176:179], v133 offset:32768
	ds_read_b128 v[180:183], v133 offset:33792
	ds_read_b128 v[186:189], v133 offset:34816
	ds_read_b128 v[190:193], v133 offset:35840
	ds_read_b128 v[194:197], v133 offset:36864
	ds_read_b128 v[198:201], v133 offset:37888
	ds_read_b128 v[202:205], v133 offset:38912
	ds_read_b128 v[206:209], v133 offset:39936
	s_waitcnt vmcnt(8)
	s_waitcnt lgkmcnt(0)
	s_barrier
	s_setprio 1
	v_mfma_f32_16x16x128_f8f6f4 v[126:129], v[138:145], v[176:183], v[126:129]
	v_mfma_f32_16x16x128_f8f6f4 v[118:121], v[138:145], v[186:193], v[118:121]
	v_mfma_f32_16x16x128_f8f6f4 v[102:105], v[138:145], v[194:201], v[102:105]
	v_mfma_f32_16x16x128_f8f6f4 v[86:89], v[138:145], v[202:209], v[86:89]
	v_mfma_f32_16x16x128_f8f6f4 v[122:125], v[146:153], v[176:183], v[122:125]
	v_mfma_f32_16x16x128_f8f6f4 v[114:117], v[146:153], v[186:193], v[114:117]
	v_mfma_f32_16x16x128_f8f6f4 v[98:101], v[146:153], v[194:201], v[98:101]
	v_mfma_f32_16x16x128_f8f6f4 v[82:85], v[146:153], v[202:209], v[82:85]
	s_setprio 0
	s_setprio 1
	v_mfma_f32_16x16x128_f8f6f4 v[110:113], v[154:161], v[176:183], v[110:113]
	v_mfma_f32_16x16x128_f8f6f4 v[94:97], v[154:161], v[186:193], v[94:97]
	v_mfma_f32_16x16x128_f8f6f4 v[78:81], v[154:161], v[194:201], v[78:81]
	v_mfma_f32_16x16x128_f8f6f4 v[62:65], v[154:161], v[202:209], v[62:65]
	v_mfma_f32_16x16x128_f8f6f4 v[106:109], v[162:169], v[176:183], v[106:109]
	v_mfma_f32_16x16x128_f8f6f4 v[90:93], v[162:169], v[186:193], v[90:93]
	v_mfma_f32_16x16x128_f8f6f4 v[74:77], v[162:169], v[194:201], v[74:77]
	v_mfma_f32_16x16x128_f8f6f4 v[42:45], v[162:169], v[202:209], v[42:45]
	s_setprio 0
	s_barrier
	ds_read_b128 v[176:179], v133 offset:49152
	ds_read_b128 v[180:183], v133 offset:50176
	ds_read_b128 v[186:189], v133 offset:51200
	ds_read_b128 v[190:193], v133 offset:52224
	ds_read_b128 v[194:197], v133 offset:53248
	ds_read_b128 v[198:201], v133 offset:54272
	ds_read_b128 v[202:205], v133 offset:55296
	ds_read_b128 v[206:209], v133 offset:56320
	s_add_u32 s36, s38, 0x80
	s_addc_u32 s37, s39, 0
	s_mov_b32 m0, s78
	s_nop 4
	global_load_lds_dwordx4 v131, s[36:37]
	s_add_u32 s36, s38, 0x2c080
	s_addc_u32 s37, s39, 0
	s_mov_b32 m0, s79
	s_nop 4
	global_load_lds_dwordx4 v131, s[36:37]
	s_add_u32 s36, s38, 0x58080
	s_addc_u32 s37, s39, 0
	s_mov_b32 m0, s82
	s_nop 4
	global_load_lds_dwordx4 v131, s[36:37]
	s_add_u32 s36, s38, 0x84080
	s_addc_u32 s37, s39, 0
	s_mov_b32 m0, s83
	s_nop 4
	global_load_lds_dwordx4 v131, s[36:37]
	s_mov_b32 m0, s80
	s_nop 4
	global_load_lds_dwordx4 v130, s[42:43]
	s_add_u32 s36, s40, 0x2c080
	s_addc_u32 s37, s41, 0
	s_mov_b32 m0, s81
	s_nop 4
	global_load_lds_dwordx4 v130, s[36:37]
	s_waitcnt vmcnt(8)
	s_waitcnt lgkmcnt(0)
	s_barrier
	s_setprio 1
	v_mfma_f32_16x16x128_f8f6f4 v[70:73], v[138:145], v[176:183], v[70:73]
	v_mfma_f32_16x16x128_f8f6f4 v[50:53], v[138:145], v[186:193], v[50:53]
	v_mfma_f32_16x16x128_f8f6f4 v[22:25], v[138:145], v[194:201], v[22:25]
	v_mfma_f32_16x16x128_f8f6f4 v[54:57], v[138:145], v[202:209], v[54:57]
	v_mfma_f32_16x16x128_f8f6f4 v[66:69], v[146:153], v[176:183], v[66:69]
	v_mfma_f32_16x16x128_f8f6f4 v[38:41], v[146:153], v[186:193], v[38:41]
	v_mfma_f32_16x16x128_f8f6f4 v[18:21], v[146:153], v[194:201], v[18:21]
	v_mfma_f32_16x16x128_f8f6f4 v[46:49], v[146:153], v[202:209], v[46:49]
	s_setprio 0
	s_setprio 1
	v_mfma_f32_16x16x128_f8f6f4 v[30:33], v[154:161], v[176:183], v[30:33]
	v_mfma_f32_16x16x128_f8f6f4 v[14:17], v[154:161], v[186:193], v[14:17]
	v_mfma_f32_16x16x128_f8f6f4 v[6:9], v[154:161], v[194:201], v[6:9]
	v_mfma_f32_16x16x128_f8f6f4 v[170:173], v[154:161], v[202:209], v[170:173]
	v_mfma_f32_16x16x128_f8f6f4 v[26:29], v[162:169], v[176:183], v[26:29]
	v_mfma_f32_16x16x128_f8f6f4 v[10:13], v[162:169], v[186:193], v[10:13]
	v_mfma_f32_16x16x128_f8f6f4 v[2:5], v[162:169], v[194:201], v[2:5]
	v_mfma_f32_16x16x128_f8f6f4 v[34:37], v[162:169], v[202:209], v[34:37]
	s_setprio 0
	s_add_i32 s87, s87, 2
	s_add_u32 s85, s85, 0x100
	s_addc_u32 s86, s86, 0
	s_cmp_lt_u32 s87, 20
	s_mov_b64 s[36:37], s[34:35]
	s_barrier
	s_cbranch_scc1 .LBB0_1493
	s_waitcnt vmcnt(0)
	s_cmpk_gt_u32 s62, 0xff
	s_cbranch_scc1 .LBB0_1496
	s_barrier
